# P5 out-proj epilogue residual x loads nt
# baseline (speedup 1.0000x reference)
; __device__ __forceinline__ unsigned cvt_pk_bf16_v(float lo, float hi) { const f32x2c v = {lo, hi}; const bf16x2c b = __builtin_convertvector(v, bf16x2c); return __builtin_bit_cast(unsigned, b); }
;     __device__ __forceinline__ void operator()(const f32x4 (&acc)[2][2][4][2], const Unit& u_, int wr, int wc, int fr, int fq) const {
;     ...
;         const int rowb = u.pm * BM + wr * 64 + (l >> 3); const int colb = u.pn * BM + wc * 32 + 4 * (l & 7);
; #pragma unroll
;         for (int ai = 0; ai < 2; ++ai) {
;             f32x4 xr[4][2][2];
; #pragma unroll
;             for (int m = 0; m < 4; ++m)
; #pragma unroll
;                 for (int bj = 0; bj < 2; ++bj)
; #pragma unroll
;                     for (int t = 0; t < 2; ++t) xr[m][bj][t] = *(const f32x4*)(xp + (size_t)(rowb + ai * HALF + m * 16 + 8 * t) * 1024 + colb + bj * HALF);
;             asm volatile("" ::: "memory");
; #pragma unroll
;             for (int m = 0; m < 4; ++m)
; #pragma unroll
;                 for (int bj = 0; bj < 2; ++bj) { f32x4 o[2]; xchg_f32(xl, fr, fq, l, acc[ai][bj][m][0], acc[ai][bj][m][1], o[0], o[1]);
; #pragma unroll
;                     for (int t = 0; t < 2; ++t) { const f32x4 v = o[t] + xr[m][bj][t]; u32x2 w; w.x = cvt_pk_bf16_v(v[0], v[1]); w.y = cvt_pk_bf16_v(v[2], v[3]);
;                         *(u32x2*)(h1b + (size_t)(rowb + ai * HALF + m * 16 + 8 * t) * 1024 + colb + bj * HALF) = w; } }
;             asm volatile("" ::: "memory");
.LBB0_836:
	s_mov_b64 s[56:57], -1
	v_lshl_add_u32 v206, s8, 8, v233
	v_lshl_or_b32 v222, s9, 8, v234
	v_ashrrev_i32_e32 v223, 31, v222
	v_ashrrev_i32_e32 v207, 31, v206
	v_lshl_add_u64 v[204:205], v[222:223], 2, s[68:69]
	v_lshlrev_b64 v[130:131], 12, v[206:207]
	v_or_b32_e32 v220, 8, v206
	v_lshl_add_u64 v[130:131], v[204:205], 0, v[130:131]
	v_ashrrev_i32_e32 v221, 31, v220
	global_load_dwordx4 v[238:241], v[130:131], off nt
	v_lshlrev_b64 v[132:133], 12, v[220:221]
	v_lshl_add_u64 v[132:133], v[204:205], 0, v[132:133]
	global_load_dwordx4 v[242:245], v[132:133], off nt
	global_load_dwordx4 v[178:181], v[130:131], off offset:512 nt
	global_load_dwordx4 v[182:185], v[132:133], off offset:512 nt
	v_or_b32_e32 v218, 16, v206
	v_ashrrev_i32_e32 v219, 31, v218
	v_lshlrev_b64 v[130:131], 12, v[218:219]
	v_lshl_add_u64 v[130:131], v[204:205], 0, v[130:131]
	global_load_dwordx4 v[174:177], v[130:131], off nt
	v_or_b32_e32 v216, 24, v206
	v_ashrrev_i32_e32 v217, 31, v216
	v_lshlrev_b64 v[132:133], 12, v[216:217]
	v_lshl_add_u64 v[132:133], v[204:205], 0, v[132:133]
	global_load_dwordx4 v[170:173], v[132:133], off nt
	global_load_dwordx4 v[166:169], v[130:131], off offset:512 nt
	global_load_dwordx4 v[162:165], v[132:133], off offset:512 nt
	v_or_b32_e32 v212, 32, v206
	v_ashrrev_i32_e32 v213, 31, v212
	v_lshlrev_b64 v[130:131], 12, v[212:213]
	v_lshl_add_u64 v[130:131], v[204:205], 0, v[130:131]
	global_load_dwordx4 v[154:157], v[130:131], off nt
	v_or_b32_e32 v214, 40, v206
	v_ashrrev_i32_e32 v215, 31, v214
	v_lshlrev_b64 v[132:133], 12, v[214:215]
	v_lshl_add_u64 v[132:133], v[204:205], 0, v[132:133]
	global_load_dwordx4 v[158:161], v[132:133], off nt
	global_load_dwordx4 v[146:149], v[130:131], off offset:512 nt
	global_load_dwordx4 v[142:145], v[132:133], off offset:512 nt
	v_or_b32_e32 v208, 48, v206
	v_ashrrev_i32_e32 v209, 31, v208
	v_lshlrev_b64 v[130:131], 12, v[208:209]
	v_lshl_add_u64 v[130:131], v[204:205], 0, v[130:131]
	global_load_dwordx4 v[138:141], v[130:131], off nt
	v_or_b32_e32 v210, 56, v206
	v_ashrrev_i32_e32 v211, 31, v210
	v_lshlrev_b64 v[132:133], 12, v[210:211]
	v_lshl_add_u64 v[132:133], v[204:205], 0, v[132:133]
	global_load_dwordx4 v[150:153], v[132:133], off nt
	global_load_dwordx4 v[134:137], v[130:131], off offset:512 nt
	s_nop 0
	global_load_dwordx4 v[130:133], v[132:133], off offset:512 nt
	ds_write_b128 v236, v[126:129]
	ds_write_b128 v236, v[122:125] offset:16
	ds_read_b128 v[122:125], v237
	ds_read_b128 v[126:129], v237 offset:1152
	s_cmp_eq_u32 s74, s72
	s_waitcnt vmcnt(0) lgkmcnt(0)
	v_pk_add_f32 v[122:123], v[238:239], v[122:123]
	v_pk_add_f32 v[128:129], v[244:245], v[128:129]
	v_pk_add_f32 v[126:127], v[242:243], v[126:127]
	v_pk_add_f32 v[124:125], v[240:241], v[124:125]
	v_cvt_pk_bf16_f32 v238, v122, v123
	v_lshlrev_b64 v[122:123], 11, v[206:207]
	v_cvt_pk_bf16_f32 v126, v126, v127
	v_cvt_pk_bf16_f32 v127, v128, v129
	v_lshlrev_b64 v[128:129], 11, v[220:221]
	v_cvt_pk_bf16_f32 v239, v124, v125
	v_lshl_add_u64 v[124:125], s[14:15], 0, v[122:123]
	v_lshlrev_b64 v[122:123], 1, v[222:223]
	v_lshl_add_u64 v[128:129], s[14:15], 0, v[128:129]
	v_lshl_add_u64 v[124:125], v[124:125], 0, v[122:123]
	v_lshl_add_u64 v[128:129], v[128:129], 0, v[122:123]
	global_store_dwordx2 v[124:125], v[238:239], off
	global_store_dwordx2 v[128:129], v[126:127], off
	ds_write_b128 v236, v[118:121]
	ds_write_b128 v236, v[114:117] offset:16
	ds_read_b128 v[114:117], v237
	ds_read_b128 v[118:121], v237 offset:1152
	s_waitcnt lgkmcnt(1)
	v_pk_add_f32 v[116:117], v[180:181], v[116:117]
	v_pk_add_f32 v[114:115], v[178:179], v[114:115]
	s_nop 0
	v_cvt_pk_bf16_f32 v114, v114, v115
	v_cvt_pk_bf16_f32 v115, v116, v117
	global_store_dwordx2 v[124:125], v[114:115], off offset:256
	s_waitcnt lgkmcnt(0)
	v_pk_add_f32 v[114:115], v[184:185], v[120:121]
	v_pk_add_f32 v[116:117], v[182:183], v[118:119]
	s_nop 0
	v_cvt_pk_bf16_f32 v116, v116, v117
	v_cvt_pk_bf16_f32 v117, v114, v115
	global_store_dwordx2 v[128:129], v[116:117], off offset:256
	ds_write_b128 v236, v[110:113]
	ds_write_b128 v236, v[106:109] offset:16
	ds_read_b128 v[106:109], v237
	ds_read_b128 v[110:113], v237 offset:1152
	s_waitcnt lgkmcnt(1)
	v_pk_add_f32 v[108:109], v[176:177], v[108:109]
	v_pk_add_f32 v[106:107], v[174:175], v[106:107]
	s_waitcnt lgkmcnt(0)
	v_pk_add_f32 v[110:111], v[170:171], v[110:111]
	v_cvt_pk_bf16_f32 v106, v106, v107
	v_cvt_pk_bf16_f32 v107, v108, v109
	v_lshlrev_b64 v[108:109], 11, v[218:219]
	v_lshl_add_u64 v[108:109], s[14:15], 0, v[108:109]
	v_lshl_add_u64 v[108:109], v[108:109], 0, v[122:123]
	global_store_dwordx2 v[108:109], v[106:107], off
	v_pk_add_f32 v[106:107], v[172:173], v[112:113]
	v_cvt_pk_bf16_f32 v110, v110, v111
	v_cvt_pk_bf16_f32 v111, v106, v107
	v_lshlrev_b64 v[106:107], 11, v[216:217]
	v_lshl_add_u64 v[106:107], s[14:15], 0, v[106:107]
	v_lshl_add_u64 v[106:107], v[106:107], 0, v[122:123]
	global_store_dwordx2 v[106:107], v[110:111], off
	ds_write_b128 v236, v[102:105]
	ds_write_b128 v236, v[98:101] offset:16
	ds_read_b128 v[98:101], v237
	ds_read_b128 v[102:105], v237 offset:1152
	s_waitcnt lgkmcnt(1)
	v_pk_add_f32 v[100:101], v[168:169], v[100:101]
	v_pk_add_f32 v[98:99], v[166:167], v[98:99]
	s_nop 0
	v_cvt_pk_bf16_f32 v98, v98, v99
	v_cvt_pk_bf16_f32 v99, v100, v101
	global_store_dwordx2 v[108:109], v[98:99], off offset:256
	s_waitcnt lgkmcnt(0)
	v_pk_add_f32 v[98:99], v[164:165], v[104:105]
	v_pk_add_f32 v[100:101], v[162:163], v[102:103]
	v_add_u32_e32 v104, 0xa0, v206
	v_cvt_pk_bf16_f32 v100, v100, v101
	v_cvt_pk_bf16_f32 v101, v98, v99
	global_store_dwordx2 v[106:107], v[100:101], off offset:256
	ds_write_b128 v236, v[94:97]
	ds_write_b128 v236, v[90:93] offset:16
	ds_read_b128 v[90:93], v237
	ds_read_b128 v[94:97], v237 offset:1152
	v_ashrrev_i32_e32 v105, 31, v104
	v_add_u32_e32 v102, 0xa8, v206
	v_ashrrev_i32_e32 v103, 31, v102
	s_waitcnt lgkmcnt(1)
; __device__ __forceinline__ unsigned cvt_pk_bf16_v(float lo, float hi) { const f32x2c v = {lo, hi}; const bf16x2c b = __builtin_convertvector(v, bf16x2c); return __builtin_bit_cast(unsigned, b); }
;     __device__ __forceinline__ void operator()(const f32x4 (&acc)[2][2][4][2], const Unit& u_, int wr, int wc, int fr, int fq) const {
;     ...
;                     for (int t = 0; t < 2; ++t) xr[m][bj][t] = *(const f32x4*)(xp + (size_t)(rowb + ai * HALF + m * 16 + 8 * t) * 1024 + colb + bj * HALF);
;             asm volatile("" ::: "memory");
; #pragma unroll
;             for (int m = 0; m < 4; ++m)
; #pragma unroll
;                 for (int bj = 0; bj < 2; ++bj) { f32x4 o[2]; xchg_f32(xl, fr, fq, l, acc[ai][bj][m][0], acc[ai][bj][m][1], o[0], o[1]);
; #pragma unroll
;                     for (int t = 0; t < 2; ++t) { const f32x4 v = o[t] + xr[m][bj][t]; u32x2 w; w.x = cvt_pk_bf16_v(v[0], v[1]); w.y = cvt_pk_bf16_v(v[2], v[3]);
;                         *(u32x2*)(h1b + (size_t)(rowb + ai * HALF + m * 16 + 8 * t) * 1024 + colb + bj * HALF) = w; } }
	v_pk_add_f32 v[92:93], v[156:157], v[92:93]
	v_pk_add_f32 v[90:91], v[154:155], v[90:91]
	s_waitcnt lgkmcnt(0)
	v_pk_add_f32 v[94:95], v[158:159], v[94:95]
	v_cvt_pk_bf16_f32 v90, v90, v91
	v_cvt_pk_bf16_f32 v91, v92, v93
	v_lshlrev_b64 v[92:93], 11, v[212:213]
	v_lshl_add_u64 v[92:93], s[14:15], 0, v[92:93]
	v_lshl_add_u64 v[92:93], v[92:93], 0, v[122:123]
	global_store_dwordx2 v[92:93], v[90:91], off
	v_pk_add_f32 v[90:91], v[160:161], v[96:97]
	v_cvt_pk_bf16_f32 v94, v94, v95
	v_cvt_pk_bf16_f32 v95, v90, v91
	v_lshlrev_b64 v[90:91], 11, v[214:215]
	v_lshl_add_u64 v[90:91], s[14:15], 0, v[90:91]
	v_lshl_add_u64 v[90:91], v[90:91], 0, v[122:123]
	global_store_dwordx2 v[90:91], v[94:95], off
	ds_write_b128 v236, v[86:89]
	ds_write_b128 v236, v[82:85] offset:16
	ds_read_b128 v[82:85], v237
	ds_read_b128 v[86:89], v237 offset:1152
	v_add_u32_e32 v100, 0xb0, v206
	v_ashrrev_i32_e32 v101, 31, v100
	v_add_u32_e32 v98, 0xb8, v206
	s_waitcnt lgkmcnt(1)
	v_pk_add_f32 v[84:85], v[148:149], v[84:85]
	v_pk_add_f32 v[82:83], v[146:147], v[82:83]
	v_add_u32_e32 v146, 0x98, v206
	v_cvt_pk_bf16_f32 v82, v82, v83
	v_cvt_pk_bf16_f32 v83, v84, v85
	global_store_dwordx2 v[92:93], v[82:83], off offset:256
	s_waitcnt lgkmcnt(0)
	v_pk_add_f32 v[82:83], v[144:145], v[88:89]
	v_pk_add_f32 v[84:85], v[142:143], v[86:87]
	v_add_u32_e32 v142, 0x88, v206
	v_cvt_pk_bf16_f32 v84, v84, v85
	v_cvt_pk_bf16_f32 v85, v82, v83
	global_store_dwordx2 v[90:91], v[84:85], off offset:256
	ds_write_b128 v236, v[78:81]
	ds_write_b128 v236, v[74:77] offset:16
	ds_read_b128 v[74:77], v237
	ds_read_b128 v[78:81], v237 offset:1152
	v_ashrrev_i32_e32 v143, 31, v142
	v_add_u32_e32 v144, 0x90, v206
	v_ashrrev_i32_e32 v145, 31, v144
	s_waitcnt lgkmcnt(1)
	v_pk_add_f32 v[76:77], v[140:141], v[76:77]
	v_pk_add_f32 v[74:75], v[138:139], v[74:75]
	s_waitcnt lgkmcnt(0)
	v_pk_add_f32 v[78:79], v[150:151], v[78:79]
	v_cvt_pk_bf16_f32 v74, v74, v75
	v_cvt_pk_bf16_f32 v75, v76, v77
	v_lshlrev_b64 v[76:77], 11, v[208:209]
	v_lshl_add_u64 v[76:77], s[14:15], 0, v[76:77]
	v_lshl_add_u64 v[76:77], v[76:77], 0, v[122:123]
	global_store_dwordx2 v[76:77], v[74:75], off
	v_pk_add_f32 v[74:75], v[152:153], v[80:81]
	v_cvt_pk_bf16_f32 v78, v78, v79
	v_cvt_pk_bf16_f32 v79, v74, v75
	v_lshlrev_b64 v[74:75], 11, v[210:211]
	v_lshl_add_u64 v[74:75], s[14:15], 0, v[74:75]
	v_lshl_add_u64 v[74:75], v[74:75], 0, v[122:123]
	global_store_dwordx2 v[74:75], v[78:79], off
	ds_write_b128 v236, v[70:73]
	ds_write_b128 v236, v[66:69] offset:16
	ds_read_b128 v[66:69], v237
	ds_read_b128 v[70:73], v237 offset:1152
	v_add_u32_e32 v140, 0x80, v206
	v_ashrrev_i32_e32 v141, 31, v140
	v_ashrrev_i32_e32 v147, 31, v146
	s_waitcnt lgkmcnt(1)
	v_pk_add_f32 v[68:69], v[136:137], v[68:69]
	v_pk_add_f32 v[66:67], v[134:135], v[66:67]
	v_ashrrev_i32_e32 v99, 31, v98
	v_cvt_pk_bf16_f32 v66, v66, v67
	v_cvt_pk_bf16_f32 v67, v68, v69
	global_store_dwordx2 v[76:77], v[66:67], off offset:256
	s_waitcnt lgkmcnt(0)
	v_pk_add_f32 v[66:67], v[132:133], v[72:73]
	v_pk_add_f32 v[68:69], v[130:131], v[70:71]
	s_nop 0
	v_cvt_pk_bf16_f32 v68, v68, v69
	v_cvt_pk_bf16_f32 v69, v66, v67
	global_store_dwordx2 v[74:75], v[68:69], off offset:256
	v_lshlrev_b64 v[66:67], 12, v[140:141]
	v_lshl_add_u64 v[66:67], v[204:205], 0, v[66:67]
	global_load_dwordx4 v[106:109], v[66:67], off nt
	v_lshlrev_b64 v[68:69], 12, v[142:143]
	v_lshl_add_u64 v[68:69], v[204:205], 0, v[68:69]
	global_load_dwordx4 v[110:113], v[68:69], off nt
	global_load_dwordx4 v[114:117], v[66:67], off offset:512 nt
	global_load_dwordx4 v[118:121], v[68:69], off offset:512 nt
	v_lshlrev_b64 v[66:67], 12, v[144:145]
	v_lshl_add_u64 v[66:67], v[204:205], 0, v[66:67]
	global_load_dwordx4 v[124:127], v[66:67], off nt
	v_lshlrev_b64 v[68:69], 12, v[146:147]
	v_lshl_add_u64 v[68:69], v[204:205], 0, v[68:69]
	global_load_dwordx4 v[128:131], v[68:69], off nt
	global_load_dwordx4 v[132:135], v[66:67], off offset:512 nt
	global_load_dwordx4 v[136:139], v[68:69], off offset:512 nt
	v_lshlrev_b64 v[66:67], 12, v[104:105]
	v_lshl_add_u64 v[66:67], v[204:205], 0, v[66:67]
	global_load_dwordx4 v[94:97], v[66:67], off nt
	v_lshlrev_b64 v[68:69], 12, v[102:103]
	v_lshl_add_u64 v[68:69], v[204:205], 0, v[68:69]
	global_load_dwordx4 v[90:93], v[68:69], off nt
	global_load_dwordx4 v[86:89], v[66:67], off offset:512 nt
	global_load_dwordx4 v[82:85], v[68:69], off offset:512 nt
	v_lshlrev_b64 v[66:67], 12, v[100:101]
	v_lshl_add_u64 v[66:67], v[204:205], 0, v[66:67]
	global_load_dwordx4 v[78:81], v[66:67], off nt
	v_lshlrev_b64 v[68:69], 12, v[98:99]
	v_lshl_add_u64 v[68:69], v[204:205], 0, v[68:69]
	global_load_dwordx4 v[74:77], v[68:69], off nt
	global_load_dwordx4 v[70:73], v[66:67], off offset:512 nt
	s_nop 0
	global_load_dwordx4 v[66:69], v[68:69], off offset:512 nt
	ds_write_b128 v236, v[62:65]
	ds_write_b128 v236, v[58:61] offset:16
	ds_read_b128 v[58:61], v237
	ds_read_b128 v[62:65], v237 offset:1152
	s_waitcnt vmcnt(15) lgkmcnt(1)
	v_pk_add_f32 v[60:61], v[108:109], v[60:61]
	v_pk_add_f32 v[58:59], v[106:107], v[58:59]
	s_waitcnt vmcnt(14) lgkmcnt(0)
	v_pk_add_f32 v[62:63], v[110:111], v[62:63]
	v_cvt_pk_bf16_f32 v58, v58, v59
	v_cvt_pk_bf16_f32 v59, v60, v61
	v_lshlrev_b64 v[60:61], 11, v[140:141]
	v_lshl_add_u64 v[60:61], s[14:15], 0, v[60:61]
	v_lshl_add_u64 v[60:61], v[60:61], 0, v[122:123]
	global_store_dwordx2 v[60:61], v[58:59], off
	v_pk_add_f32 v[58:59], v[112:113], v[64:65]
	v_cvt_pk_bf16_f32 v62, v62, v63
	v_cvt_pk_bf16_f32 v63, v58, v59
	v_lshlrev_b64 v[58:59], 11, v[142:143]
	v_lshl_add_u64 v[58:59], s[14:15], 0, v[58:59]
	v_lshl_add_u64 v[58:59], v[58:59], 0, v[122:123]
	global_store_dwordx2 v[58:59], v[62:63], off
	ds_write_b128 v236, v[54:57]
	ds_write_b128 v236, v[50:53] offset:16
	ds_read_b128 v[50:53], v237
	ds_read_b128 v[54:57], v237 offset:1152
	s_waitcnt vmcnt(15) lgkmcnt(1)
; __device__ __forceinline__ unsigned cvt_pk_bf16_v(float lo, float hi) { const f32x2c v = {lo, hi}; const bf16x2c b = __builtin_convertvector(v, bf16x2c); return __builtin_bit_cast(unsigned, b); }
; #define PG8_BAR __builtin_amdgcn_s_barrier()
;     __device__ __forceinline__ void operator()(const f32x4 (&acc)[2][2][4][2], const Unit& u_, int wr, int wc, int fr, int fq) const {
;     ...
;             for (int m = 0; m < 4; ++m)
; #pragma unroll
;                 for (int bj = 0; bj < 2; ++bj) { f32x4 o[2]; xchg_f32(xl, fr, fq, l, acc[ai][bj][m][0], acc[ai][bj][m][1], o[0], o[1]);
; #pragma unroll
;                     for (int t = 0; t < 2; ++t) { const f32x4 v = o[t] + xr[m][bj][t]; u32x2 w; w.x = cvt_pk_bf16_v(v[0], v[1]); w.y = cvt_pk_bf16_v(v[2], v[3]);
;                         *(u32x2*)(h1b + (size_t)(rowb + ai * HALF + m * 16 + 8 * t) * 1024 + colb + bj * HALF) = w; } }
;             asm volatile("" ::: "memory");
; template <class Epi, class Sched, bool ALIGN_EPI = false, bool SP2 = false>
; __device__ __forceinline__ void gemm_phase(PG8_LAS unsigned char* lds, const Gemm g, const Sched& S, const Epi& E) {
;     ...
;         if constexpr (ALIGN_EPI) { if (wr == 1) PG8_BAR; }
	v_pk_add_f32 v[52:53], v[116:117], v[52:53]
	v_pk_add_f32 v[50:51], v[114:115], v[50:51]
	s_nop 0
	v_cvt_pk_bf16_f32 v50, v50, v51
	v_cvt_pk_bf16_f32 v51, v52, v53
	global_store_dwordx2 v[60:61], v[50:51], off offset:256
	s_waitcnt vmcnt(15) lgkmcnt(0)
	v_pk_add_f32 v[50:51], v[120:121], v[56:57]
	v_pk_add_f32 v[52:53], v[118:119], v[54:55]
	s_nop 0
	v_cvt_pk_bf16_f32 v52, v52, v53
	v_cvt_pk_bf16_f32 v53, v50, v51
	global_store_dwordx2 v[58:59], v[52:53], off offset:256
	ds_write_b128 v236, v[46:49]
	ds_write_b128 v236, v[42:45] offset:16
	ds_read_b128 v[42:45], v237
	ds_read_b128 v[46:49], v237 offset:1152
	s_waitcnt vmcnt(15) lgkmcnt(1)
	v_pk_add_f32 v[44:45], v[126:127], v[44:45]
	v_pk_add_f32 v[42:43], v[124:125], v[42:43]
	s_waitcnt vmcnt(14) lgkmcnt(0)
	v_pk_add_f32 v[46:47], v[128:129], v[46:47]
	v_cvt_pk_bf16_f32 v42, v42, v43
	v_cvt_pk_bf16_f32 v43, v44, v45
	v_lshlrev_b64 v[44:45], 11, v[144:145]
	v_lshl_add_u64 v[44:45], s[14:15], 0, v[44:45]
	v_lshl_add_u64 v[44:45], v[44:45], 0, v[122:123]
	global_store_dwordx2 v[44:45], v[42:43], off
	v_pk_add_f32 v[42:43], v[130:131], v[48:49]
	v_cvt_pk_bf16_f32 v46, v46, v47
	v_cvt_pk_bf16_f32 v47, v42, v43
	v_lshlrev_b64 v[42:43], 11, v[146:147]
	v_lshl_add_u64 v[42:43], s[14:15], 0, v[42:43]
	v_lshl_add_u64 v[42:43], v[42:43], 0, v[122:123]
	global_store_dwordx2 v[42:43], v[46:47], off
	ds_write_b128 v236, v[38:41]
	ds_write_b128 v236, v[34:37] offset:16
	ds_read_b128 v[34:37], v237
	ds_read_b128 v[38:41], v237 offset:1152
	s_waitcnt vmcnt(15) lgkmcnt(1)
	v_pk_add_f32 v[36:37], v[134:135], v[36:37]
	v_pk_add_f32 v[34:35], v[132:133], v[34:35]
	s_nop 0
	v_cvt_pk_bf16_f32 v34, v34, v35
	v_cvt_pk_bf16_f32 v35, v36, v37
	global_store_dwordx2 v[44:45], v[34:35], off offset:256
	s_waitcnt vmcnt(15) lgkmcnt(0)
	v_pk_add_f32 v[34:35], v[138:139], v[40:41]
	v_pk_add_f32 v[36:37], v[136:137], v[38:39]
	s_nop 0
	v_cvt_pk_bf16_f32 v36, v36, v37
	v_cvt_pk_bf16_f32 v37, v34, v35
	global_store_dwordx2 v[42:43], v[36:37], off offset:256
	ds_write_b128 v236, v[30:33]
	ds_write_b128 v236, v[26:29] offset:16
	ds_read_b128 v[26:29], v237
	ds_read_b128 v[30:33], v237 offset:1152
	s_waitcnt vmcnt(15) lgkmcnt(1)
	v_pk_add_f32 v[28:29], v[96:97], v[28:29]
	v_pk_add_f32 v[26:27], v[94:95], v[26:27]
	s_waitcnt vmcnt(14) lgkmcnt(0)
	v_pk_add_f32 v[30:31], v[90:91], v[30:31]
	v_cvt_pk_bf16_f32 v26, v26, v27
	v_cvt_pk_bf16_f32 v27, v28, v29
	v_lshlrev_b64 v[28:29], 11, v[104:105]
	v_lshl_add_u64 v[28:29], s[14:15], 0, v[28:29]
	v_lshl_add_u64 v[28:29], v[28:29], 0, v[122:123]
	global_store_dwordx2 v[28:29], v[26:27], off
	v_pk_add_f32 v[26:27], v[92:93], v[32:33]
	v_cvt_pk_bf16_f32 v30, v30, v31
	v_cvt_pk_bf16_f32 v31, v26, v27
	v_lshlrev_b64 v[26:27], 11, v[102:103]
	v_lshl_add_u64 v[26:27], s[14:15], 0, v[26:27]
	v_lshl_add_u64 v[26:27], v[26:27], 0, v[122:123]
	global_store_dwordx2 v[26:27], v[30:31], off
	ds_write_b128 v236, v[22:25]
	ds_write_b128 v236, v[18:21] offset:16
	ds_read_b128 v[18:21], v237
	ds_read_b128 v[22:25], v237 offset:1152
	s_waitcnt vmcnt(15) lgkmcnt(1)
	v_pk_add_f32 v[20:21], v[88:89], v[20:21]
	v_pk_add_f32 v[18:19], v[86:87], v[18:19]
	s_nop 0
	v_cvt_pk_bf16_f32 v18, v18, v19
	v_cvt_pk_bf16_f32 v19, v20, v21
	global_store_dwordx2 v[28:29], v[18:19], off offset:256
	s_waitcnt vmcnt(15) lgkmcnt(0)
	v_pk_add_f32 v[18:19], v[84:85], v[24:25]
	v_pk_add_f32 v[20:21], v[82:83], v[22:23]
	s_nop 0
	v_cvt_pk_bf16_f32 v20, v20, v21
	v_cvt_pk_bf16_f32 v21, v18, v19
	global_store_dwordx2 v[26:27], v[20:21], off offset:256
	ds_write_b128 v236, v[14:17]
	ds_write_b128 v236, v[10:13] offset:16
	ds_read_b128 v[10:13], v237
	ds_read_b128 v[14:17], v237 offset:1152
	s_waitcnt vmcnt(15) lgkmcnt(1)
	v_pk_add_f32 v[12:13], v[80:81], v[12:13]
	v_pk_add_f32 v[10:11], v[78:79], v[10:11]
	s_waitcnt vmcnt(14) lgkmcnt(0)
	v_pk_add_f32 v[14:15], v[74:75], v[14:15]
	v_cvt_pk_bf16_f32 v10, v10, v11
	v_cvt_pk_bf16_f32 v11, v12, v13
	v_lshlrev_b64 v[12:13], 11, v[100:101]
	v_lshl_add_u64 v[12:13], s[14:15], 0, v[12:13]
	v_lshl_add_u64 v[12:13], v[12:13], 0, v[122:123]
	global_store_dwordx2 v[12:13], v[10:11], off
	v_pk_add_f32 v[10:11], v[76:77], v[16:17]
	v_cvt_pk_bf16_f32 v14, v14, v15
	v_cvt_pk_bf16_f32 v15, v10, v11
	v_lshlrev_b64 v[10:11], 11, v[98:99]
	v_lshl_add_u64 v[10:11], s[14:15], 0, v[10:11]
	v_lshl_add_u64 v[10:11], v[10:11], 0, v[122:123]
	global_store_dwordx2 v[10:11], v[14:15], off
	ds_write_b128 v236, v[6:9]
	ds_write_b128 v236, v[2:5] offset:16
	ds_read_b128 v[2:5], v237
	ds_read_b128 v[6:9], v237 offset:1152
	s_waitcnt vmcnt(15) lgkmcnt(1)
	v_pk_add_f32 v[4:5], v[72:73], v[4:5]
	v_pk_add_f32 v[2:3], v[70:71], v[2:3]
	s_nop 0
	v_cvt_pk_bf16_f32 v2, v2, v3
	v_cvt_pk_bf16_f32 v3, v4, v5
	global_store_dwordx2 v[12:13], v[2:3], off offset:256
	s_waitcnt vmcnt(15) lgkmcnt(0)
	v_pk_add_f32 v[2:3], v[68:69], v[8:9]
	v_pk_add_f32 v[4:5], v[66:67], v[6:7]
	s_nop 0
	v_cvt_pk_bf16_f32 v4, v4, v5
	v_cvt_pk_bf16_f32 v5, v2, v3
	global_store_dwordx2 v[10:11], v[4:5], off offset:256
	s_cbranch_scc1 .LBB0_831
	s_andn2_b64 vcc, exec, s[48:49]
	s_cbranch_vccnz .LBB0_830
	s_barrier
	s_branch .LBB0_830
